# stack3 + attention softmax cross-half exchanges (row max, row sum) via v_permlane32_swap instead of ds_bpermute round trips
# baseline (speedup 1.0000x reference)
; #define LAS __attribute__((address_space(3)))
; DI int crow(int r, int hi) { return (r & 3) + 8 * (r >> 2) + 4 * hi; }
; DI void qkt(f32x16& p0, f32x16& p1, const LAS char* Ks, const bf16x8* qr, int r32, int hi) {
;     for (int i = 0; i < 16; ++i) { p0[i] = 0.f; p1[i] = 0.f; }
; #pragma unroll
;     for (int d0 = 0; d0 < 8; ++d0) { const int cb = (d0 * 16 + hi * 8) * 2;
;         const bf16x8 b0 = *(const LAS bf16x8*)(Ks + KSWZ(r32, cb));
;         const bf16x8 b1 = *(const LAS bf16x8*)(Ks + KSWZ(32 + r32, cb));
;         p0 = __builtin_amdgcn_mfma_f32_32x32x16_bf16(b0, qr[d0], p0, 0, 0, 0);
;         p1 = __builtin_amdgcn_mfma_f32_32x32x16_bf16(b1, qr[d0], p1, 0, 0, 0); }
; }
; DI void phase_attn(const Params& P, int l, LAS unsigned char* lds) {
;     ...
;             for (int h2 = 0; h2 < 2; ++h2) {
;                 const int kp0 = (n - 1 + t) * 128 + h2 * 64;
;                 if (kp0 + 63 >= rq - 128 && kp0 <= rq + 159) {
;                     f32x16 p0, p1;
;                     qkt(p0, p1, Bf + h2 * 16384, qr, r32, hi);
;                     const LAS float* tq = tg + (kp0 - rq);
;                     float pmax = -1e30f;
; #pragma unroll
;                     for (int r = 0; r < 16; ++r) { p0[r] += tq[crow(r, hi)]; p1[r] += tq[32 + crow(r, hi)]; pmax = fmaxf(pmax, fmaxf(p0[r], p1[r])); }
.LBB0_486:
	s_and_b32 s25, s91, 0x10000
	s_add_i32 s24, s71, s93
	v_add_u32_e32 v66, s25, v206
	v_add_u32_e32 v223, s25, v215
	s_add_i32 s25, s24, 63
	s_cmp_lt_i32 s25, s89
	s_cselect_b64 s[26:27], -1, 0
	s_cmp_gt_i32 s24, s90
	s_cselect_b64 s[28:29], -1, 0
	s_or_b64 s[26:27], s[26:27], s[28:29]
	s_and_b64 vcc, exec, s[26:27]
	v_add_u32_e32 v232, v66, v147
	v_add_u32_e32 v231, v66, v208
	v_add_u32_e32 v230, v66, v209
	v_add_u32_e32 v229, v66, v210
	v_add_u32_e32 v228, v66, v211
	v_add_u32_e32 v227, v66, v212
	v_add_u32_e32 v226, v66, v213
	v_add_u32_e32 v225, v66, v214
	v_add_u32_e32 v224, s70, v219
	s_cbranch_vccnz .LBB0_490
	ds_read_b128 v[66:69], v232
	ds_read_b128 v[82:85], v232 offset:8192
	ds_read_b128 v[234:237], v231
	ds_read_b128 v[238:241], v231 offset:8192
	v_add_u32_e32 v233, 0x20180, v224
	v_add_u32_e32 v244, 0x20208, v224
	ds_read_b128 v[246:249], v230
	ds_read_b128 v[250:253], v230 offset:8192
	s_waitcnt lgkmcnt(4)
	v_mfma_f32_32x32x16_bf16 v[66:81], v[66:69], v[126:129], 0
	v_mfma_f32_32x32x16_bf16 v[82:97], v[82:85], v[126:129], 0
	s_waitcnt lgkmcnt(2)
	v_mfma_f32_32x32x16_bf16 v[66:81], v[234:237], v[122:125], v[66:81]
	v_mfma_f32_32x32x16_bf16 v[82:97], v[238:241], v[122:125], v[82:97]
	ds_read_b128 v[234:237], v229
	ds_read_b128 v[238:241], v229 offset:8192
	s_waitcnt lgkmcnt(2)
	v_mfma_f32_32x32x16_bf16 v[66:81], v[246:249], v[118:121], v[66:81]
	v_mfma_f32_32x32x16_bf16 v[82:97], v[250:253], v[118:121], v[82:97]
	ds_read_b128 v[246:249], v228
	ds_read_b128 v[250:253], v228 offset:8192
	s_waitcnt lgkmcnt(2)
	v_mfma_f32_32x32x16_bf16 v[66:81], v[234:237], v[114:117], v[66:81]
	v_mfma_f32_32x32x16_bf16 v[82:97], v[238:241], v[114:117], v[82:97]
	ds_read_b128 v[234:237], v227
	ds_read_b128 v[238:241], v227 offset:8192
	s_waitcnt lgkmcnt(2)
	v_mfma_f32_32x32x16_bf16 v[66:81], v[246:249], v[110:113], v[66:81]
	v_mfma_f32_32x32x16_bf16 v[82:97], v[250:253], v[110:113], v[82:97]
	ds_read_b128 v[246:249], v226
	ds_read_b128 v[250:253], v226 offset:8192
	s_waitcnt lgkmcnt(2)
	v_mfma_f32_32x32x16_bf16 v[66:81], v[234:237], v[106:109], v[66:81]
	v_mfma_f32_32x32x16_bf16 v[82:97], v[238:241], v[106:109], v[82:97]
	ds_read_b128 v[234:237], v225
	ds_read_b128 v[238:241], v225 offset:8192
	s_waitcnt lgkmcnt(2)
	v_mfma_f32_32x32x16_bf16 v[66:81], v[246:249], v[102:105], v[66:81]
	v_mfma_f32_32x32x16_bf16 v[82:97], v[250:253], v[102:105], v[82:97]
	ds_read2_b32 v[242:243], v233 offset1:1
	v_add_u32_e32 v233, 0x20200, v224
	s_waitcnt lgkmcnt(0)
	v_mfma_f32_32x32x16_bf16 v[66:81], v[234:237], v[98:101], v[66:81]
	v_add_u32_e32 v236, 0x20188, v224
	ds_read2_b32 v[234:235], v233 offset1:1
	ds_read2_b32 v[236:237], v236 offset1:1
	ds_read2_b32 v[244:245], v244 offset1:1
	v_mfma_f32_32x32x16_bf16 v[82:97], v[238:241], v[98:101], v[82:97]
	s_nop 6
	v_add_f32_e32 v233, v66, v242
	v_add_f32_e32 v238, v67, v243
	s_waitcnt lgkmcnt(0)
	v_add_f32_e32 v236, v68, v236
	v_add_f32_e32 v237, v69, v237
	v_add_f32_e32 v234, v82, v234
	v_add_f32_e32 v235, v83, v235
	v_max_f32_e32 v66, v233, v234
	v_max_f32_e32 v67, v238, v235
	v_add_f32_e32 v239, v84, v244
	v_add_f32_e32 v240, v85, v245
	v_max3_f32 v66, v66, s74, v67
	v_max_f32_e32 v67, v236, v239
	v_max_f32_e32 v68, v237, v240
	v_max3_f32 v241, v66, v67, v68
	v_add_u32_e32 v66, 0x201a0, v224
	v_add_u32_e32 v68, 0x20220, v224
	ds_read2_b32 v[66:67], v66 offset1:1
	ds_read2_b32 v[68:69], v68 offset1:1
	v_add_u32_e32 v82, 0x201a8, v224
	v_add_u32_e32 v84, 0x20228, v224
	ds_read2_b32 v[82:83], v82 offset1:1
	ds_read2_b32 v[84:85], v84 offset1:1
	s_waitcnt lgkmcnt(0)
	v_add_f32_e32 v242, v70, v66
	v_add_f32_e32 v86, v86, v68
	v_add_f32_e32 v243, v71, v67
	v_add_f32_e32 v87, v87, v69
	v_max_f32_e32 v66, v242, v86
	v_max_f32_e32 v67, v243, v87
	v_add_f32_e32 v82, v72, v82
	v_add_f32_e32 v84, v88, v84
	v_add_f32_e32 v83, v73, v83
	v_add_f32_e32 v85, v89, v85
	v_max3_f32 v66, v241, v66, v67
	v_max_f32_e32 v67, v82, v84
	v_max_f32_e32 v68, v83, v85
	v_max3_f32 v88, v66, v67, v68
	v_add_u32_e32 v66, 0x201c0, v224
	v_add_u32_e32 v68, 0x20240, v224
	ds_read2_b32 v[66:67], v66 offset1:1
	ds_read2_b32 v[68:69], v68 offset1:1
	v_add_u32_e32 v70, 0x201c8, v224
	v_add_u32_e32 v72, 0x20248, v224
	ds_read2_b32 v[70:71], v70 offset1:1
	ds_read2_b32 v[72:73], v72 offset1:1
	s_waitcnt lgkmcnt(0)
	v_add_f32_e32 v74, v74, v66
	v_add_f32_e32 v89, v90, v68
	v_add_f32_e32 v75, v75, v67
	v_add_f32_e32 v90, v91, v69
	v_max_f32_e32 v66, v74, v89
	v_max_f32_e32 v67, v75, v90
	v_max3_f32 v66, v88, v66, v67
	v_add_f32_e32 v76, v76, v70
	v_add_f32_e32 v88, v92, v72
	v_add_f32_e32 v77, v77, v71
	v_add_f32_e32 v91, v93, v73
	v_max_f32_e32 v67, v76, v88
	v_max_f32_e32 v68, v77, v91
	v_max3_f32 v92, v66, v67, v68
	v_add_u32_e32 v66, 0x201e0, v224
	v_add_u32_e32 v68, 0x20260, v224
	ds_read2_b32 v[66:67], v66 offset1:1
	ds_read2_b32 v[68:69], v68 offset1:1
	v_add_u32_e32 v70, 0x201e8, v224
	v_add_u32_e32 v72, 0x20268, v224
	ds_read2_b32 v[70:71], v70 offset1:1
	ds_read2_b32 v[72:73], v72 offset1:1
	s_waitcnt lgkmcnt(0)
; DI int crow(int r, int hi) { return (r & 3) + 8 * (r >> 2) + 4 * hi; }
; DI void phase_attn(const Params& P, int l, LAS unsigned char* lds) {
;     ...
;                     for (int r = 0; r < 16; ++r) { p0[r] += tq[crow(r, hi)]; p1[r] += tq[32 + crow(r, hi)]; pmax = fmaxf(pmax, fmaxf(p0[r], p1[r])); }
;                     pmax = fmaxf(pmax, __shfl_xor(pmax, 32));
;                     float mn = m_run, alpha = 1.f;
;                     if (!__all(pmax - m_run <= 8.f)) { mn = fmaxf(m_run, pmax); alpha = __builtin_amdgcn_exp2f(m_run - mn); m_run = mn; }
;                     float ps = 0.f;
; #pragma unroll
;                     for (int r = 0; r < 16; ++r) { p0[r] = __builtin_amdgcn_exp2f(p0[r] - mn); p1[r] = __builtin_amdgcn_exp2f(p1[r] - mn); ps += p0[r] + p1[r]; }
;                     ps += __shfl_xor(ps, 32);
;                     l_run = l_run * alpha + ps;
;                     bf16x8 pa0, pa1, pa2, pa3;
;     ...
;                     PK4(p0, 0, pa0); PK4(p0, 8, pa1); PK4(p1, 0, pa2); PK4(p1, 8, pa3);
;     ...
;                     if (__any(alpha < 1.f)) {
; #pragma unroll
;                         for (int d = 0; d < 4; ++d)
; #pragma unroll
;                             for (int r = 0; r < 16; ++r) o[d][r] *= alpha; }
	v_add_f32_e32 v66, v78, v66
	v_add_f32_e32 v68, v94, v68
	v_add_f32_e32 v67, v79, v67
	v_add_f32_e32 v69, v95, v69
	v_max_f32_e32 v78, v66, v68
	v_max_f32_e32 v79, v67, v69
	v_add_f32_e32 v70, v80, v70
	v_add_f32_e32 v72, v96, v72
	v_add_f32_e32 v71, v81, v71
	v_add_f32_e32 v73, v97, v73
	v_max3_f32 v78, v92, v78, v79
	v_max_f32_e32 v79, v70, v72
	v_max_f32_e32 v80, v71, v73
	v_max3_f32 v78, v78, v79, v80
	v_mov_b32_e32 v80, v78
	s_nop 1
	v_permlane32_swap_b32_e32 v80, v78
	v_max_f32_e32 v78, v78, v80
	v_sub_f32_e32 v80, v78, v220
	v_cmp_ge_f32_e32 vcc, s75, v80
	s_cmp_eq_u64 vcc, exec
	v_max_f32_e32 v80, v220, v220
	v_max_f32_e32 v78, v80, v78
	s_cselect_b64 vcc, -1, 0
	v_sub_f32_e32 v80, v220, v78
	v_cndmask_b32_e32 v220, v78, v220, vcc
	v_sub_f32_e32 v78, v233, v220
	v_sub_f32_e32 v81, v234, v220
	v_exp_f32_e32 v78, v78
	v_exp_f32_e32 v81, v81
	v_sub_f32_e32 v92, v238, v220
	v_sub_f32_e32 v93, v235, v220
	v_exp_f32_e32 v92, v92
	v_exp_f32_e32 v93, v93
	v_sub_f32_e32 v96, v236, v220
	v_sub_f32_e32 v97, v239, v220
	v_exp_f32_e32 v96, v96
	v_exp_f32_e32 v97, v97
	v_sub_f32_e32 v233, v237, v220
	v_sub_f32_e32 v234, v240, v220
	v_exp_f32_e32 v233, v233
	v_exp_f32_e32 v234, v234
	v_sub_f32_e32 v235, v242, v220
	v_sub_f32_e32 v86, v86, v220
	v_sub_f32_e32 v82, v82, v220
	v_add_f32_e32 v94, v78, v81
	v_exp_f32_e32 v235, v235
	v_exp_f32_e32 v86, v86
	v_sub_f32_e32 v236, v243, v220
	v_sub_f32_e32 v87, v87, v220
	v_exp_f32_e32 v237, v82
	v_sub_f32_e32 v82, v84, v220
	v_add_f32_e32 v94, 0, v94
	v_add_f32_e32 v95, v92, v93
	v_exp_f32_e32 v236, v236
	v_exp_f32_e32 v87, v87
	v_exp_f32_e32 v238, v82
	v_sub_f32_e32 v82, v83, v220
	v_add_f32_e32 v94, v95, v94
	v_add_f32_e32 v95, v96, v97
	v_exp_f32_e32 v239, v82
	v_sub_f32_e32 v82, v85, v220
	v_add_f32_e32 v94, v95, v94
	v_add_f32_e32 v95, v233, v234
	v_exp_f32_e32 v85, v82
	v_sub_f32_e32 v74, v74, v220
	v_sub_f32_e32 v84, v89, v220
	v_add_f32_e32 v94, v95, v94
	v_add_f32_e32 v95, v235, v86
	v_exp_f32_e32 v74, v74
	v_exp_f32_e32 v89, v84
	v_sub_f32_e32 v75, v75, v220
	v_sub_f32_e32 v84, v90, v220
	v_add_f32_e32 v94, v95, v94
	v_add_f32_e32 v95, v236, v87
	v_exp_f32_e32 v75, v75
	v_exp_f32_e32 v90, v84
	v_sub_f32_e32 v76, v76, v220
	v_sub_f32_e32 v84, v88, v220
	v_sub_f32_e32 v66, v66, v220
	v_add_f32_e32 v82, v95, v94
	v_add_f32_e32 v83, v237, v238
	v_exp_f32_e32 v76, v76
	v_exp_f32_e32 v88, v84
	v_sub_f32_e32 v77, v77, v220
	v_sub_f32_e32 v84, v91, v220
	v_exp_f32_e32 v94, v66
	v_sub_f32_e32 v66, v68, v220
	v_add_f32_e32 v82, v83, v82
	v_add_f32_e32 v83, v239, v85
	v_exp_f32_e32 v77, v77
	v_exp_f32_e32 v91, v84
	v_exp_f32_e32 v95, v66
	v_sub_f32_e32 v66, v67, v220
	v_sub_f32_e32 v68, v70, v220
	v_add_f32_e32 v82, v83, v82
	v_add_f32_e32 v83, v74, v89
	v_exp_f32_e32 v240, v66
	v_sub_f32_e32 v66, v69, v220
	v_exp_f32_e32 v242, v68
	v_sub_f32_e32 v68, v72, v220
	v_add_f32_e32 v82, v83, v82
	v_add_f32_e32 v83, v75, v90
	v_exp_f32_e32 v241, v66
	v_exp_f32_e32 v243, v68
	v_sub_f32_e32 v68, v71, v220
	v_add_f32_e32 v82, v83, v82
	v_add_f32_e32 v83, v76, v88
	v_exp_f32_e32 v244, v68
	v_sub_f32_e32 v68, v73, v220
	v_add_f32_e32 v82, v83, v82
	v_add_f32_e32 v83, v77, v91
	v_exp_f32_e32 v245, v68
	v_add_f32_e32 v66, v83, v82
	v_add_f32_e32 v67, v94, v95
	v_add_f32_e32 v66, v67, v66
	v_add_f32_e32 v67, v240, v241
	v_add_f32_e32 v66, v67, v66
	v_add_f32_e32 v67, v242, v243
	v_add_f32_e32 v66, v67, v66
	v_add_f32_e32 v67, v244, v245
	v_exp_f32_e32 v80, v80
	v_add_f32_e32 v83, v67, v66
	v_mov_b32_e32 v84, v83
	s_nop 1
	v_permlane32_swap_b32_e32 v84, v83
	v_cvt_pk_bf16_f32 v66, v78, v92
	v_cndmask_b32_e64 v82, v80, 1.0, vcc
	v_cvt_pk_bf16_f32 v67, v96, v233
	v_cvt_pk_bf16_f32 v68, v235, v236
	v_cvt_pk_bf16_f32 v69, v237, v239
	v_cvt_pk_bf16_f32 v70, v74, v75
	v_cvt_pk_bf16_f32 v71, v76, v77
	v_cvt_pk_bf16_f32 v72, v94, v240
	v_cvt_pk_bf16_f32 v73, v242, v244
	v_cvt_pk_bf16_f32 v74, v81, v93
	v_cvt_pk_bf16_f32 v75, v97, v234
	v_cvt_pk_bf16_f32 v76, v86, v87
	v_cvt_pk_bf16_f32 v77, v238, v85
	v_cvt_pk_bf16_f32 v78, v89, v90
	v_cvt_pk_bf16_f32 v79, v88, v91
	v_cvt_pk_bf16_f32 v80, v95, v241
	v_cvt_pk_bf16_f32 v81, v243, v245
	s_nop 0
	v_permlane32_swap_b32_e32 v66, v68
	v_permlane32_swap_b32_e32 v67, v69
	v_permlane32_swap_b32_e32 v70, v72
	v_permlane32_swap_b32_e32 v71, v73
	v_permlane32_swap_b32_e32 v74, v76
	v_permlane32_swap_b32_e32 v75, v77
	v_permlane32_swap_b32_e32 v78, v80
	v_permlane32_swap_b32_e32 v79, v81
	v_cmp_gt_f32_e32 vcc, 1.0, v82
	s_cbranch_vccz .LBB0_489
	v_pk_mul_f32 v[64:65], v[64:65], v[82:83] op_sel_hi:[1,0]
	v_pk_mul_f32 v[62:63], v[62:63], v[82:83] op_sel_hi:[1,0]
	v_pk_mul_f32 v[60:61], v[60:61], v[82:83] op_sel_hi:[1,0]
	v_pk_mul_f32 v[58:59], v[58:59], v[82:83] op_sel_hi:[1,0]
	v_pk_mul_f32 v[56:57], v[56:57], v[82:83] op_sel_hi:[1,0]
	v_pk_mul_f32 v[54:55], v[54:55], v[82:83] op_sel_hi:[1,0]
	v_pk_mul_f32 v[52:53], v[52:53], v[82:83] op_sel_hi:[1,0]
	v_pk_mul_f32 v[50:51], v[50:51], v[82:83] op_sel_hi:[1,0]
	v_pk_mul_f32 v[48:49], v[48:49], v[82:83] op_sel_hi:[1,0]
	v_pk_mul_f32 v[46:47], v[46:47], v[82:83] op_sel_hi:[1,0]
	v_pk_mul_f32 v[44:45], v[44:45], v[82:83] op_sel_hi:[1,0]
	v_pk_mul_f32 v[42:43], v[42:43], v[82:83] op_sel_hi:[1,0]
	v_pk_mul_f32 v[40:41], v[40:41], v[82:83] op_sel_hi:[1,0]
	v_pk_mul_f32 v[38:39], v[38:39], v[82:83] op_sel_hi:[1,0]
	v_pk_mul_f32 v[36:37], v[36:37], v[82:83] op_sel_hi:[1,0]
	v_pk_mul_f32 v[34:35], v[34:35], v[82:83] op_sel_hi:[1,0]
	v_pk_mul_f32 v[32:33], v[32:33], v[82:83] op_sel_hi:[1,0]
	v_pk_mul_f32 v[30:31], v[30:31], v[82:83] op_sel_hi:[1,0]
	v_pk_mul_f32 v[28:29], v[28:29], v[82:83] op_sel_hi:[1,0]
	v_pk_mul_f32 v[26:27], v[26:27], v[82:83] op_sel_hi:[1,0]
	v_pk_mul_f32 v[24:25], v[24:25], v[82:83] op_sel_hi:[1,0]
	v_pk_mul_f32 v[22:23], v[22:23], v[82:83] op_sel_hi:[1,0]
	v_pk_mul_f32 v[20:21], v[20:21], v[82:83] op_sel_hi:[1,0]
	v_pk_mul_f32 v[18:19], v[18:19], v[82:83] op_sel_hi:[1,0]
	v_pk_mul_f32 v[16:17], v[16:17], v[82:83] op_sel_hi:[1,0]
	v_pk_mul_f32 v[14:15], v[14:15], v[82:83] op_sel_hi:[1,0]
	v_pk_mul_f32 v[12:13], v[12:13], v[82:83] op_sel_hi:[1,0]
	v_pk_mul_f32 v[10:11], v[10:11], v[82:83] op_sel_hi:[1,0]
	v_pk_mul_f32 v[8:9], v[8:9], v[82:83] op_sel_hi:[1,0]
	v_pk_mul_f32 v[6:7], v[6:7], v[82:83] op_sel_hi:[1,0]
	v_pk_mul_f32 v[4:5], v[4:5], v[82:83] op_sel_hi:[1,0]
	v_pk_mul_f32 v[2:3], v[2:3], v[82:83] op_sel_hi:[1,0]

; #define LAS __attribute__((address_space(3)))
; DI int crow(int r, int hi) { return (r & 3) + 8 * (r >> 2) + 4 * hi; }
; DI void qkt(f32x16& p0, f32x16& p1, const LAS char* Ks, const bf16x8* qr, int r32, int hi) {
;     for (int i = 0; i < 16; ++i) { p0[i] = 0.f; p1[i] = 0.f; }
; #pragma unroll
;     for (int d0 = 0; d0 < 8; ++d0) { const int cb = (d0 * 16 + hi * 8) * 2;
;         const bf16x8 b0 = *(const LAS bf16x8*)(Ks + KSWZ(r32, cb));
;         const bf16x8 b1 = *(const LAS bf16x8*)(Ks + KSWZ(32 + r32, cb));
;         p0 = __builtin_amdgcn_mfma_f32_32x32x16_bf16(b0, qr[d0], p0, 0, 0, 0);
;         p1 = __builtin_amdgcn_mfma_f32_32x32x16_bf16(b1, qr[d0], p1, 0, 0, 0); }
; }
; DI void phase_attn(const Params& P, int l, LAS unsigned char* lds) {
;     ...
;             for (int h2 = 0; h2 < 2; ++h2) {
;                 const int kp0 = (n - 1 + t) * 128 + h2 * 64;
;                 if (kp0 + 63 >= rq - 128 && kp0 <= rq + 159) {
;                     f32x16 p0, p1;
;                     qkt(p0, p1, Bf + h2 * 16384, qr, r32, hi);
;                     const LAS float* tq = tg + (kp0 - rq);
;                     float pmax = -1e30f;
; #pragma unroll
;                     for (int r = 0; r < 16; ++r) { p0[r] += tq[crow(r, hi)]; p1[r] += tq[32 + crow(r, hi)]; pmax = fmaxf(pmax, fmaxf(p0[r], p1[r])); }
.LBB0_490:
	s_add_i32 s26, s24, 64
	s_addk_i32 s24, 0x7f
	s_cmp_lt_i32 s24, s89
	s_cselect_b64 s[24:25], -1, 0
	s_cmp_gt_i32 s26, s90
	s_cselect_b64 s[26:27], -1, 0
	s_or_b64 s[24:25], s[24:25], s[26:27]
	s_and_b64 vcc, exec, s[24:25]
	s_cbranch_vccnz .LBB0_474
	ds_read_b128 v[66:69], v232 offset:16384
	ds_read_b128 v[82:85], v232 offset:24576
	ds_read_b128 v[232:235], v231 offset:16384
	ds_read_b128 v[236:239], v231 offset:24576
	ds_read_b128 v[246:249], v230 offset:16384
	ds_read_b128 v[250:253], v230 offset:24576
	s_waitcnt lgkmcnt(4)
	v_mfma_f32_32x32x16_bf16 v[66:81], v[66:69], v[126:129], 0
	v_mfma_f32_32x32x16_bf16 v[82:97], v[82:85], v[126:129], 0
	s_waitcnt lgkmcnt(2)
	v_mfma_f32_32x32x16_bf16 v[66:81], v[232:235], v[122:125], v[66:81]
	v_mfma_f32_32x32x16_bf16 v[82:97], v[236:239], v[122:125], v[82:97]
	ds_read_b128 v[230:233], v229 offset:16384
	ds_read_b128 v[234:237], v229 offset:24576
	s_waitcnt lgkmcnt(2)
	v_mfma_f32_32x32x16_bf16 v[66:81], v[246:249], v[118:121], v[66:81]
	v_mfma_f32_32x32x16_bf16 v[82:97], v[250:253], v[118:121], v[82:97]
	ds_read_b128 v[246:249], v228 offset:16384
	ds_read_b128 v[250:253], v228 offset:24576
	s_waitcnt lgkmcnt(2)
	v_mfma_f32_32x32x16_bf16 v[66:81], v[230:233], v[114:117], v[66:81]
	v_mfma_f32_32x32x16_bf16 v[82:97], v[234:237], v[114:117], v[82:97]
	ds_read_b128 v[228:231], v227 offset:16384
	ds_read_b128 v[232:235], v227 offset:24576
	s_waitcnt lgkmcnt(2)
	v_mfma_f32_32x32x16_bf16 v[66:81], v[246:249], v[110:113], v[66:81]
	v_mfma_f32_32x32x16_bf16 v[82:97], v[250:253], v[110:113], v[82:97]
	ds_read_b128 v[246:249], v226 offset:16384
	ds_read_b128 v[250:253], v226 offset:24576
	v_add_u32_e32 v236, 0x20308, v224
	s_waitcnt lgkmcnt(2)
	v_mfma_f32_32x32x16_bf16 v[66:81], v[228:231], v[106:109], v[66:81]
	v_mfma_f32_32x32x16_bf16 v[82:97], v[232:235], v[106:109], v[82:97]
	ds_read_b128 v[226:229], v225 offset:16384
	ds_read_b128 v[230:233], v225 offset:24576
	s_waitcnt lgkmcnt(2)
	v_mfma_f32_32x32x16_bf16 v[66:81], v[246:249], v[102:105], v[66:81]
	v_mfma_f32_32x32x16_bf16 v[82:97], v[250:253], v[102:105], v[82:97]
	v_add_u32_e32 v225, 0x20280, v224
	ds_read2_b32 v[234:235], v225 offset1:1
	v_add_u32_e32 v225, 0x20300, v224
	s_waitcnt lgkmcnt(0)
	v_mfma_f32_32x32x16_bf16 v[66:81], v[226:229], v[98:101], v[66:81]
	v_add_u32_e32 v228, 0x20288, v224
	ds_read2_b32 v[226:227], v225 offset1:1
	ds_read2_b32 v[228:229], v228 offset1:1
	ds_read2_b32 v[236:237], v236 offset1:1
	v_mfma_f32_32x32x16_bf16 v[82:97], v[230:233], v[98:101], v[82:97]
	s_nop 6
	v_add_f32_e32 v225, v66, v234
	v_add_f32_e32 v230, v67, v235
	s_waitcnt lgkmcnt(0)
	v_add_f32_e32 v228, v68, v228
	v_add_f32_e32 v229, v69, v229
	v_add_f32_e32 v226, v82, v226
	v_add_f32_e32 v227, v83, v227
	v_max_f32_e32 v66, v225, v226
	v_max_f32_e32 v67, v230, v227
	v_add_f32_e32 v231, v84, v236
	v_add_f32_e32 v232, v85, v237
	v_max3_f32 v66, v66, s74, v67
	v_max_f32_e32 v67, v228, v231
	v_max_f32_e32 v68, v229, v232
	v_max3_f32 v233, v66, v67, v68
	v_add_u32_e32 v66, 0x202a0, v224
	v_add_u32_e32 v68, 0x20320, v224
	ds_read2_b32 v[66:67], v66 offset1:1
	ds_read2_b32 v[68:69], v68 offset1:1
	v_add_u32_e32 v82, 0x202a8, v224
	v_add_u32_e32 v84, 0x20328, v224
	ds_read2_b32 v[82:83], v82 offset1:1
	ds_read2_b32 v[84:85], v84 offset1:1
	s_waitcnt lgkmcnt(0)
	v_add_f32_e32 v234, v70, v66
	v_add_f32_e32 v86, v86, v68
	v_add_f32_e32 v235, v71, v67
	v_add_f32_e32 v87, v87, v69
	v_max_f32_e32 v66, v234, v86
	v_max_f32_e32 v67, v235, v87
	v_add_f32_e32 v82, v72, v82
	v_add_f32_e32 v84, v88, v84
	v_add_f32_e32 v83, v73, v83
	v_add_f32_e32 v85, v89, v85
	v_max3_f32 v66, v233, v66, v67
	v_max_f32_e32 v67, v82, v84
	v_max_f32_e32 v68, v83, v85
	v_max3_f32 v88, v66, v67, v68
	v_add_u32_e32 v66, 0x202c0, v224
	v_add_u32_e32 v68, 0x20340, v224
	ds_read2_b32 v[66:67], v66 offset1:1
	ds_read2_b32 v[68:69], v68 offset1:1
	v_add_u32_e32 v70, 0x202c8, v224
	v_add_u32_e32 v72, 0x20348, v224
	ds_read2_b32 v[70:71], v70 offset1:1
	ds_read2_b32 v[72:73], v72 offset1:1
	s_waitcnt lgkmcnt(0)
	v_add_f32_e32 v74, v74, v66
	v_add_f32_e32 v89, v90, v68
	v_add_f32_e32 v75, v75, v67
	v_add_f32_e32 v90, v91, v69
	v_max_f32_e32 v66, v74, v89
	v_max_f32_e32 v67, v75, v90
	v_max3_f32 v66, v88, v66, v67
	v_add_f32_e32 v76, v76, v70
	v_add_f32_e32 v88, v92, v72
	v_add_f32_e32 v77, v77, v71
	v_add_f32_e32 v91, v93, v73
	v_max_f32_e32 v67, v76, v88
	v_max_f32_e32 v68, v77, v91
	v_max3_f32 v92, v66, v67, v68
	v_add_u32_e32 v66, 0x202e0, v224
	v_add_u32_e32 v68, 0x20360, v224
	ds_read2_b32 v[66:67], v66 offset1:1
	ds_read2_b32 v[68:69], v68 offset1:1
	v_add_u32_e32 v70, 0x202e8, v224
	v_add_u32_e32 v72, 0x20368, v224
	ds_read2_b32 v[70:71], v70 offset1:1
	ds_read2_b32 v[72:73], v72 offset1:1
	s_waitcnt lgkmcnt(0)
; DI int crow(int r, int hi) { return (r & 3) + 8 * (r >> 2) + 4 * hi; }
; DI void phase_attn(const Params& P, int l, LAS unsigned char* lds) {
;     ...
;                     for (int r = 0; r < 16; ++r) { p0[r] += tq[crow(r, hi)]; p1[r] += tq[32 + crow(r, hi)]; pmax = fmaxf(pmax, fmaxf(p0[r], p1[r])); }
;                     pmax = fmaxf(pmax, __shfl_xor(pmax, 32));
;                     float mn = m_run, alpha = 1.f;
;                     if (!__all(pmax - m_run <= 8.f)) { mn = fmaxf(m_run, pmax); alpha = __builtin_amdgcn_exp2f(m_run - mn); m_run = mn; }
;                     float ps = 0.f;
; #pragma unroll
;                     for (int r = 0; r < 16; ++r) { p0[r] = __builtin_amdgcn_exp2f(p0[r] - mn); p1[r] = __builtin_amdgcn_exp2f(p1[r] - mn); ps += p0[r] + p1[r]; }
;                     ps += __shfl_xor(ps, 32);
;                     l_run = l_run * alpha + ps;
;                     bf16x8 pa0, pa1, pa2, pa3;
;     ...
;                     PK4(p0, 0, pa0); PK4(p0, 8, pa1); PK4(p1, 0, pa2); PK4(p1, 8, pa3);
;     ...
;                     if (__any(alpha < 1.f)) {
; #pragma unroll
;                         for (int d = 0; d < 4; ++d)
; #pragma unroll
;                             for (int r = 0; r < 16; ++r) o[d][r] *= alpha; }
	v_add_f32_e32 v66, v78, v66
	v_add_f32_e32 v68, v94, v68
	v_add_f32_e32 v67, v79, v67
	v_add_f32_e32 v69, v95, v69
	v_max_f32_e32 v78, v66, v68
	v_max_f32_e32 v79, v67, v69
	v_add_f32_e32 v70, v80, v70
	v_add_f32_e32 v72, v96, v72
	v_add_f32_e32 v71, v81, v71
	v_add_f32_e32 v73, v97, v73
	v_max3_f32 v78, v92, v78, v79
	v_max_f32_e32 v79, v70, v72
	v_max_f32_e32 v80, v71, v73
	v_max3_f32 v78, v78, v79, v80
	v_mov_b32_e32 v80, v78
	s_nop 1
	v_permlane32_swap_b32_e32 v80, v78
	v_max_f32_e32 v78, v78, v80
	v_sub_f32_e32 v80, v78, v220
	v_cmp_ge_f32_e32 vcc, s75, v80
	s_cmp_eq_u64 vcc, exec
	v_max_f32_e32 v80, v220, v220
	v_max_f32_e32 v78, v80, v78
	s_cselect_b64 vcc, -1, 0
	v_sub_f32_e32 v80, v220, v78
	v_cndmask_b32_e32 v220, v78, v220, vcc
	v_sub_f32_e32 v78, v225, v220
	v_sub_f32_e32 v81, v226, v220
	v_exp_f32_e32 v78, v78
	v_exp_f32_e32 v81, v81
	v_sub_f32_e32 v92, v230, v220
	v_sub_f32_e32 v93, v227, v220
	v_exp_f32_e32 v92, v92
	v_exp_f32_e32 v93, v93
	v_sub_f32_e32 v96, v228, v220
	v_sub_f32_e32 v97, v231, v220
	v_exp_f32_e32 v96, v96
	v_exp_f32_e32 v97, v97
	v_sub_f32_e32 v224, v229, v220
	v_sub_f32_e32 v225, v232, v220
	v_exp_f32_e32 v224, v224
	v_exp_f32_e32 v225, v225
	v_sub_f32_e32 v226, v234, v220
	v_sub_f32_e32 v86, v86, v220
	v_sub_f32_e32 v82, v82, v220
	v_add_f32_e32 v94, v78, v81
	v_exp_f32_e32 v226, v226
	v_exp_f32_e32 v86, v86
	v_sub_f32_e32 v227, v235, v220
	v_sub_f32_e32 v87, v87, v220
	v_exp_f32_e32 v228, v82
	v_sub_f32_e32 v82, v84, v220
	v_add_f32_e32 v94, 0, v94
	v_add_f32_e32 v95, v92, v93
	v_exp_f32_e32 v227, v227
	v_exp_f32_e32 v87, v87
	v_exp_f32_e32 v229, v82
	v_sub_f32_e32 v82, v83, v220
	v_add_f32_e32 v94, v95, v94
	v_add_f32_e32 v95, v96, v97
	v_exp_f32_e32 v230, v82
	v_sub_f32_e32 v82, v85, v220
	v_add_f32_e32 v94, v95, v94
	v_add_f32_e32 v95, v224, v225
	v_exp_f32_e32 v85, v82
	v_sub_f32_e32 v74, v74, v220
	v_sub_f32_e32 v84, v89, v220
	v_add_f32_e32 v94, v95, v94
	v_add_f32_e32 v95, v226, v86
	v_exp_f32_e32 v74, v74
	v_exp_f32_e32 v89, v84
	v_sub_f32_e32 v75, v75, v220
	v_sub_f32_e32 v84, v90, v220
	v_add_f32_e32 v94, v95, v94
	v_add_f32_e32 v95, v227, v87
	v_exp_f32_e32 v75, v75
	v_exp_f32_e32 v90, v84
	v_sub_f32_e32 v76, v76, v220
	v_sub_f32_e32 v84, v88, v220
	v_sub_f32_e32 v66, v66, v220
	v_add_f32_e32 v82, v95, v94
	v_add_f32_e32 v83, v228, v229
	v_exp_f32_e32 v76, v76
	v_exp_f32_e32 v88, v84
	v_sub_f32_e32 v77, v77, v220
	v_sub_f32_e32 v84, v91, v220
	v_exp_f32_e32 v94, v66
	v_sub_f32_e32 v66, v68, v220
	v_add_f32_e32 v82, v83, v82
	v_add_f32_e32 v83, v230, v85
	v_exp_f32_e32 v77, v77
	v_exp_f32_e32 v91, v84
	v_exp_f32_e32 v95, v66
	v_sub_f32_e32 v66, v67, v220
	v_sub_f32_e32 v68, v70, v220
	v_add_f32_e32 v82, v83, v82
	v_add_f32_e32 v83, v74, v89
	v_exp_f32_e32 v231, v66
	v_sub_f32_e32 v66, v69, v220
	v_exp_f32_e32 v233, v68
	v_sub_f32_e32 v68, v72, v220
	v_add_f32_e32 v82, v83, v82
	v_add_f32_e32 v83, v75, v90
	v_exp_f32_e32 v232, v66
	v_exp_f32_e32 v234, v68
	v_sub_f32_e32 v68, v71, v220
	v_add_f32_e32 v82, v83, v82
	v_add_f32_e32 v83, v76, v88
	v_exp_f32_e32 v235, v68
	v_sub_f32_e32 v68, v73, v220
	v_add_f32_e32 v82, v83, v82
	v_add_f32_e32 v83, v77, v91
	v_exp_f32_e32 v236, v68
	v_add_f32_e32 v66, v83, v82
	v_add_f32_e32 v67, v94, v95
	v_add_f32_e32 v66, v67, v66
	v_add_f32_e32 v67, v231, v232
	v_add_f32_e32 v66, v67, v66
	v_add_f32_e32 v67, v233, v234
	v_add_f32_e32 v66, v67, v66
	v_add_f32_e32 v67, v235, v236
	v_exp_f32_e32 v80, v80
	v_add_f32_e32 v83, v67, v66
	v_mov_b32_e32 v84, v83
	s_nop 1
	v_permlane32_swap_b32_e32 v84, v83
	v_cvt_pk_bf16_f32 v66, v78, v92
	v_cndmask_b32_e64 v82, v80, 1.0, vcc
	v_cvt_pk_bf16_f32 v67, v96, v224
	v_cvt_pk_bf16_f32 v68, v226, v227
	v_cvt_pk_bf16_f32 v69, v228, v230
	v_cvt_pk_bf16_f32 v70, v74, v75
	v_cvt_pk_bf16_f32 v71, v76, v77
	v_cvt_pk_bf16_f32 v72, v94, v231
	v_cvt_pk_bf16_f32 v73, v233, v235
	v_cvt_pk_bf16_f32 v74, v81, v93
	v_cvt_pk_bf16_f32 v75, v97, v225
	v_cvt_pk_bf16_f32 v76, v86, v87
	v_cvt_pk_bf16_f32 v77, v229, v85
	v_cvt_pk_bf16_f32 v78, v89, v90
	v_cvt_pk_bf16_f32 v79, v88, v91
	v_cvt_pk_bf16_f32 v80, v95, v232
	v_cvt_pk_bf16_f32 v81, v234, v236
	s_nop 0
	v_permlane32_swap_b32_e32 v66, v68
	v_permlane32_swap_b32_e32 v67, v69
	v_permlane32_swap_b32_e32 v70, v72
	v_permlane32_swap_b32_e32 v71, v73
	v_permlane32_swap_b32_e32 v74, v76
	v_permlane32_swap_b32_e32 v75, v77
	v_permlane32_swap_b32_e32 v78, v80
	v_permlane32_swap_b32_e32 v79, v81
	v_cmp_gt_f32_e32 vcc, 1.0, v82
	s_cbranch_vccz .LBB0_473
	v_pk_mul_f32 v[64:65], v[64:65], v[82:83] op_sel_hi:[1,0]
	v_pk_mul_f32 v[62:63], v[62:63], v[82:83] op_sel_hi:[1,0]
	v_pk_mul_f32 v[60:61], v[60:61], v[82:83] op_sel_hi:[1,0]
	v_pk_mul_f32 v[58:59], v[58:59], v[82:83] op_sel_hi:[1,0]
	v_pk_mul_f32 v[56:57], v[56:57], v[82:83] op_sel_hi:[1,0]
	v_pk_mul_f32 v[54:55], v[54:55], v[82:83] op_sel_hi:[1,0]
	v_pk_mul_f32 v[52:53], v[52:53], v[82:83] op_sel_hi:[1,0]
	v_pk_mul_f32 v[50:51], v[50:51], v[82:83] op_sel_hi:[1,0]
	v_pk_mul_f32 v[48:49], v[48:49], v[82:83] op_sel_hi:[1,0]
	v_pk_mul_f32 v[46:47], v[46:47], v[82:83] op_sel_hi:[1,0]
	v_pk_mul_f32 v[44:45], v[44:45], v[82:83] op_sel_hi:[1,0]
	v_pk_mul_f32 v[42:43], v[42:43], v[82:83] op_sel_hi:[1,0]
	v_pk_mul_f32 v[40:41], v[40:41], v[82:83] op_sel_hi:[1,0]
	v_pk_mul_f32 v[38:39], v[38:39], v[82:83] op_sel_hi:[1,0]
	v_pk_mul_f32 v[36:37], v[36:37], v[82:83] op_sel_hi:[1,0]
	v_pk_mul_f32 v[34:35], v[34:35], v[82:83] op_sel_hi:[1,0]
	v_pk_mul_f32 v[32:33], v[32:33], v[82:83] op_sel_hi:[1,0]
	v_pk_mul_f32 v[30:31], v[30:31], v[82:83] op_sel_hi:[1,0]
	v_pk_mul_f32 v[28:29], v[28:29], v[82:83] op_sel_hi:[1,0]
	v_pk_mul_f32 v[26:27], v[26:27], v[82:83] op_sel_hi:[1,0]
	v_pk_mul_f32 v[24:25], v[24:25], v[82:83] op_sel_hi:[1,0]
	v_pk_mul_f32 v[22:23], v[22:23], v[82:83] op_sel_hi:[1,0]
	v_pk_mul_f32 v[20:21], v[20:21], v[82:83] op_sel_hi:[1,0]
	v_pk_mul_f32 v[18:19], v[18:19], v[82:83] op_sel_hi:[1,0]
	v_pk_mul_f32 v[16:17], v[16:17], v[82:83] op_sel_hi:[1,0]
	v_pk_mul_f32 v[14:15], v[14:15], v[82:83] op_sel_hi:[1,0]
	v_pk_mul_f32 v[12:13], v[12:13], v[82:83] op_sel_hi:[1,0]
	v_pk_mul_f32 v[10:11], v[10:11], v[82:83] op_sel_hi:[1,0]
	v_pk_mul_f32 v[8:9], v[8:9], v[82:83] op_sel_hi:[1,0]
	v_pk_mul_f32 v[6:7], v[6:7], v[82:83] op_sel_hi:[1,0]
	v_pk_mul_f32 v[4:5], v[4:5], v[82:83] op_sel_hi:[1,0]
	v_pk_mul_f32 v[2:3], v[2:3], v[82:83] op_sel_hi:[1,0]
	s_branch .LBB0_473

; #define LAS __attribute__((address_space(3)))
; DI int crow(int r, int hi) { return (r & 3) + 8 * (r >> 2) + 4 * hi; }
; DI void qkt(f32x16& p0, f32x16& p1, const LAS char* Ks, const bf16x8* qr, int r32, int hi) {
;     for (int i = 0; i < 16; ++i) { p0[i] = 0.f; p1[i] = 0.f; }
; #pragma unroll
;     for (int d0 = 0; d0 < 8; ++d0) { const int cb = (d0 * 16 + hi * 8) * 2;
;         const bf16x8 b0 = *(const LAS bf16x8*)(Ks + KSWZ(r32, cb));
;         const bf16x8 b1 = *(const LAS bf16x8*)(Ks + KSWZ(32 + r32, cb));
;         p0 = __builtin_amdgcn_mfma_f32_32x32x16_bf16(b0, qr[d0], p0, 0, 0, 0);
;         p1 = __builtin_amdgcn_mfma_f32_32x32x16_bf16(b1, qr[d0], p1, 0, 0, 0); }
; }
; DI void phase_attn(const Params& P, int l, LAS unsigned char* lds) {
;     ...
;             for (int h2 = 0; h2 < 2; ++h2) {
;                 const int kp0 = (n - 1 + t) * 128 + h2 * 64;
;                 if (kp0 + 63 >= rq - 128 && kp0 <= rq + 159) {
;                     f32x16 p0, p1;
;                     qkt(p0, p1, Bf + h2 * 16384, qr, r32, hi);
;                     const LAS float* tq = tg + (kp0 - rq);
;                     float pmax = -1e30f;
; #pragma unroll
;                     for (int r = 0; r < 16; ++r) { p0[r] += tq[crow(r, hi)]; p1[r] += tq[32 + crow(r, hi)]; pmax = fmaxf(pmax, fmaxf(p0[r], p1[r])); }
.LBB0_1048:
	s_and_b32 s29, s88, 0x10000
	s_add_i32 s28, s71, s90
	v_add_u32_e32 v66, s29, v203
	v_add_u32_e32 v220, s29, v212
	s_add_i32 s29, s28, 63
	s_cmp_lt_i32 s29, s86
	s_cselect_b64 s[30:31], -1, 0
	s_cmp_gt_i32 s28, s87
	s_cselect_b64 s[34:35], -1, 0
	s_or_b64 s[30:31], s[30:31], s[34:35]
	s_and_b64 vcc, exec, s[30:31]
	v_add_u32_e32 v229, v66, v202
	v_add_u32_e32 v228, v66, v205
	v_add_u32_e32 v227, v66, v206
	v_add_u32_e32 v226, v66, v207
	v_add_u32_e32 v225, v66, v208
	v_add_u32_e32 v224, v66, v209
	v_add_u32_e32 v223, v66, v210
	v_add_u32_e32 v222, v66, v211
	v_add_u32_e32 v221, s70, v216
	s_cbranch_vccnz .LBB0_1052
	ds_read_b128 v[66:69], v229
	ds_read_b128 v[82:85], v229 offset:8192
	ds_read_b128 v[230:233], v228
	ds_read_b128 v[234:237], v228 offset:8192
	v_add_u32_e32 v238, 0x20180, v221
	v_add_u32_e32 v240, 0x20208, v221
	ds_read_b128 v[246:249], v227
	ds_read_b128 v[250:253], v227 offset:8192
	s_waitcnt lgkmcnt(4)
	v_mfma_f32_32x32x16_bf16 v[66:81], v[66:69], v[126:129], 0
	v_mfma_f32_32x32x16_bf16 v[82:97], v[82:85], v[126:129], 0
	s_waitcnt lgkmcnt(2)
	v_mfma_f32_32x32x16_bf16 v[66:81], v[230:233], v[122:125], v[66:81]
	v_mfma_f32_32x32x16_bf16 v[82:97], v[234:237], v[122:125], v[82:97]
	ds_read_b128 v[230:233], v226
	ds_read_b128 v[234:237], v226 offset:8192
	s_waitcnt lgkmcnt(2)
	v_mfma_f32_32x32x16_bf16 v[66:81], v[246:249], v[118:121], v[66:81]
	v_mfma_f32_32x32x16_bf16 v[82:97], v[250:253], v[118:121], v[82:97]
	ds_read_b128 v[246:249], v225
	ds_read_b128 v[250:253], v225 offset:8192
	s_waitcnt lgkmcnt(2)
	v_mfma_f32_32x32x16_bf16 v[66:81], v[230:233], v[114:117], v[66:81]
	v_mfma_f32_32x32x16_bf16 v[82:97], v[234:237], v[114:117], v[82:97]
	ds_read_b128 v[230:233], v224
	ds_read_b128 v[234:237], v224 offset:8192
	s_waitcnt lgkmcnt(2)
	v_mfma_f32_32x32x16_bf16 v[66:81], v[246:249], v[110:113], v[66:81]
	v_mfma_f32_32x32x16_bf16 v[82:97], v[250:253], v[110:113], v[82:97]
	ds_read_b128 v[246:249], v223
	ds_read_b128 v[250:253], v223 offset:8192
	s_waitcnt lgkmcnt(2)
	v_mfma_f32_32x32x16_bf16 v[66:81], v[230:233], v[106:109], v[66:81]
	v_mfma_f32_32x32x16_bf16 v[82:97], v[234:237], v[106:109], v[82:97]
	ds_read_b128 v[230:233], v222
	ds_read_b128 v[234:237], v222 offset:8192
	s_waitcnt lgkmcnt(2)
	v_mfma_f32_32x32x16_bf16 v[66:81], v[246:249], v[102:105], v[66:81]
	v_mfma_f32_32x32x16_bf16 v[82:97], v[250:253], v[102:105], v[82:97]
	ds_read2_b32 v[238:239], v238 offset1:1
	s_waitcnt lgkmcnt(0)
	v_mfma_f32_32x32x16_bf16 v[66:81], v[230:233], v[98:101], v[66:81]
	v_add_u32_e32 v230, 0x20200, v221
	v_add_u32_e32 v232, 0x20188, v221
	ds_read2_b32 v[230:231], v230 offset1:1
	ds_read2_b32 v[232:233], v232 offset1:1
	ds_read2_b32 v[240:241], v240 offset1:1
	s_nop 6
	v_add_f32_e32 v238, v66, v238
	v_mfma_f32_32x32x16_bf16 v[82:97], v[234:237], v[98:101], v[82:97]
	v_add_f32_e32 v234, v67, v239
	s_waitcnt lgkmcnt(0)
	v_add_f32_e32 v232, v68, v232
	v_add_f32_e32 v233, v69, v233
	s_nop 7
	v_add_f32_e32 v230, v82, v230
	v_add_f32_e32 v231, v83, v231
	v_max_f32_e32 v66, v238, v230
	v_max_f32_e32 v67, v234, v231
	v_add_f32_e32 v235, v84, v240
	v_add_f32_e32 v236, v85, v241
	v_max3_f32 v66, v66, s57, v67
	v_max_f32_e32 v67, v232, v235
	v_max_f32_e32 v68, v233, v236
	v_max3_f32 v237, v66, v67, v68
	v_add_u32_e32 v66, 0x201a0, v221
	v_add_u32_e32 v68, 0x20220, v221
	ds_read2_b32 v[66:67], v66 offset1:1
	ds_read2_b32 v[68:69], v68 offset1:1
	v_add_u32_e32 v82, 0x201a8, v221
	v_add_u32_e32 v84, 0x20228, v221
	ds_read2_b32 v[82:83], v82 offset1:1
	ds_read2_b32 v[84:85], v84 offset1:1
	s_waitcnt lgkmcnt(0)
	v_add_f32_e32 v239, v70, v66
	v_add_f32_e32 v86, v86, v68
	v_add_f32_e32 v240, v71, v67
	v_add_f32_e32 v87, v87, v69
	v_max_f32_e32 v66, v239, v86
	v_max_f32_e32 v67, v240, v87
	v_add_f32_e32 v82, v72, v82
	v_add_f32_e32 v84, v88, v84
	v_add_f32_e32 v83, v73, v83
	v_add_f32_e32 v85, v89, v85
	v_max3_f32 v66, v237, v66, v67
	v_max_f32_e32 v67, v82, v84
	v_max_f32_e32 v68, v83, v85
	v_max3_f32 v88, v66, v67, v68
	v_add_u32_e32 v66, 0x201c0, v221
	v_add_u32_e32 v68, 0x20240, v221
	ds_read2_b32 v[66:67], v66 offset1:1
	ds_read2_b32 v[68:69], v68 offset1:1
	v_add_u32_e32 v70, 0x201c8, v221
	v_add_u32_e32 v72, 0x20248, v221
	ds_read2_b32 v[70:71], v70 offset1:1
	ds_read2_b32 v[72:73], v72 offset1:1
	s_waitcnt lgkmcnt(0)
	v_add_f32_e32 v74, v74, v66
	v_add_f32_e32 v89, v90, v68
	v_add_f32_e32 v75, v75, v67
	v_add_f32_e32 v90, v91, v69
	v_max_f32_e32 v66, v74, v89
	v_max_f32_e32 v67, v75, v90
	v_max3_f32 v66, v88, v66, v67
	v_add_f32_e32 v76, v76, v70
	v_add_f32_e32 v88, v92, v72
	v_add_f32_e32 v77, v77, v71
	v_add_f32_e32 v91, v93, v73
	v_max_f32_e32 v67, v76, v88
	v_max_f32_e32 v68, v77, v91
	v_max3_f32 v92, v66, v67, v68
	v_add_u32_e32 v66, 0x201e0, v221
	v_add_u32_e32 v68, 0x20260, v221
	ds_read2_b32 v[66:67], v66 offset1:1
	ds_read2_b32 v[68:69], v68 offset1:1
	v_add_u32_e32 v70, 0x201e8, v221
	v_add_u32_e32 v72, 0x20268, v221
	ds_read2_b32 v[70:71], v70 offset1:1
	ds_read2_b32 v[72:73], v72 offset1:1
	s_waitcnt lgkmcnt(0)
; DI int crow(int r, int hi) { return (r & 3) + 8 * (r >> 2) + 4 * hi; }
; DI void phase_attn(const Params& P, int l, LAS unsigned char* lds) {
;     ...
;                     for (int r = 0; r < 16; ++r) { p0[r] += tq[crow(r, hi)]; p1[r] += tq[32 + crow(r, hi)]; pmax = fmaxf(pmax, fmaxf(p0[r], p1[r])); }
;                     pmax = fmaxf(pmax, __shfl_xor(pmax, 32));
;                     float mn = m_run, alpha = 1.f;
;                     if (!__all(pmax - m_run <= 8.f)) { mn = fmaxf(m_run, pmax); alpha = __builtin_amdgcn_exp2f(m_run - mn); m_run = mn; }
;                     float ps = 0.f;
; #pragma unroll
;                     for (int r = 0; r < 16; ++r) { p0[r] = __builtin_amdgcn_exp2f(p0[r] - mn); p1[r] = __builtin_amdgcn_exp2f(p1[r] - mn); ps += p0[r] + p1[r]; }
;                     ps += __shfl_xor(ps, 32);
;                     l_run = l_run * alpha + ps;
;                     bf16x8 pa0, pa1, pa2, pa3;
;     ...
;                     PK4(p0, 0, pa0); PK4(p0, 8, pa1); PK4(p1, 0, pa2); PK4(p1, 8, pa3);
;     ...
;                     if (__any(alpha < 1.f)) {
; #pragma unroll
;                         for (int d = 0; d < 4; ++d)
; #pragma unroll
;                             for (int r = 0; r < 16; ++r) o[d][r] *= alpha; }
	v_add_f32_e32 v66, v78, v66
	v_add_f32_e32 v68, v94, v68
	v_add_f32_e32 v67, v79, v67
	v_add_f32_e32 v69, v95, v69
	v_max_f32_e32 v78, v66, v68
	v_max_f32_e32 v79, v67, v69
	v_add_f32_e32 v70, v80, v70
	v_add_f32_e32 v72, v96, v72
	v_add_f32_e32 v71, v81, v71
	v_add_f32_e32 v73, v97, v73
	v_max3_f32 v78, v92, v78, v79
	v_max_f32_e32 v79, v70, v72
	v_max_f32_e32 v80, v71, v73
	v_max3_f32 v78, v78, v79, v80
	v_mov_b32_e32 v80, v78
	s_nop 1
	v_permlane32_swap_b32_e32 v80, v78
	v_max_f32_e32 v78, v78, v80
	v_sub_f32_e32 v80, v78, v217
	v_cmp_ge_f32_e32 vcc, s58, v80
	s_cmp_eq_u64 vcc, exec
	v_max_f32_e32 v80, v217, v217
	v_max_f32_e32 v78, v80, v78
	s_cselect_b64 vcc, -1, 0
	v_sub_f32_e32 v80, v217, v78
	v_cndmask_b32_e32 v217, v78, v217, vcc
	v_sub_f32_e32 v78, v238, v217
	v_sub_f32_e32 v81, v230, v217
	v_exp_f32_e32 v78, v78
	v_exp_f32_e32 v81, v81
	v_sub_f32_e32 v92, v234, v217
	v_sub_f32_e32 v93, v231, v217
	v_exp_f32_e32 v92, v92
	v_exp_f32_e32 v93, v93
	v_sub_f32_e32 v96, v232, v217
	v_sub_f32_e32 v97, v235, v217
	v_exp_f32_e32 v96, v96
	v_exp_f32_e32 v97, v97
	v_sub_f32_e32 v230, v233, v217
	v_sub_f32_e32 v231, v236, v217
	v_exp_f32_e32 v230, v230
	v_exp_f32_e32 v231, v231
	v_sub_f32_e32 v232, v239, v217
	v_sub_f32_e32 v86, v86, v217
	v_sub_f32_e32 v82, v82, v217
	v_add_f32_e32 v94, v78, v81
	v_exp_f32_e32 v232, v232
	v_exp_f32_e32 v86, v86
	v_sub_f32_e32 v233, v240, v217
	v_sub_f32_e32 v87, v87, v217
	v_exp_f32_e32 v234, v82
	v_sub_f32_e32 v82, v84, v217
	v_add_f32_e32 v94, 0, v94
	v_add_f32_e32 v95, v92, v93
	v_exp_f32_e32 v233, v233
	v_exp_f32_e32 v87, v87
	v_exp_f32_e32 v235, v82
	v_sub_f32_e32 v82, v83, v217
	v_add_f32_e32 v94, v95, v94
	v_add_f32_e32 v95, v96, v97
	v_exp_f32_e32 v236, v82
	v_sub_f32_e32 v82, v85, v217
	v_add_f32_e32 v94, v95, v94
	v_add_f32_e32 v95, v230, v231
	v_exp_f32_e32 v85, v82
	v_sub_f32_e32 v74, v74, v217
	v_sub_f32_e32 v84, v89, v217
	v_add_f32_e32 v94, v95, v94
	v_add_f32_e32 v95, v232, v86
	v_exp_f32_e32 v74, v74
	v_exp_f32_e32 v89, v84
	v_sub_f32_e32 v75, v75, v217
	v_sub_f32_e32 v84, v90, v217
	v_add_f32_e32 v94, v95, v94
	v_add_f32_e32 v95, v233, v87
	v_exp_f32_e32 v75, v75
	v_exp_f32_e32 v90, v84
	v_sub_f32_e32 v76, v76, v217
	v_sub_f32_e32 v84, v88, v217
	v_sub_f32_e32 v66, v66, v217
	v_add_f32_e32 v82, v95, v94
	v_add_f32_e32 v83, v234, v235
	v_exp_f32_e32 v76, v76
	v_exp_f32_e32 v88, v84
	v_sub_f32_e32 v77, v77, v217
	v_sub_f32_e32 v84, v91, v217
	v_exp_f32_e32 v94, v66
	v_sub_f32_e32 v66, v68, v217
	v_add_f32_e32 v82, v83, v82
	v_add_f32_e32 v83, v236, v85
	v_exp_f32_e32 v77, v77
	v_exp_f32_e32 v91, v84
	v_exp_f32_e32 v95, v66
	v_sub_f32_e32 v66, v67, v217
	v_sub_f32_e32 v68, v70, v217
	v_add_f32_e32 v82, v83, v82
	v_add_f32_e32 v83, v74, v89
	v_exp_f32_e32 v237, v66
	v_sub_f32_e32 v66, v69, v217
	v_exp_f32_e32 v239, v68
	v_sub_f32_e32 v68, v72, v217
	v_add_f32_e32 v82, v83, v82
	v_add_f32_e32 v83, v75, v90
	v_exp_f32_e32 v238, v66
	v_exp_f32_e32 v240, v68
	v_sub_f32_e32 v68, v71, v217
	v_add_f32_e32 v82, v83, v82
	v_add_f32_e32 v83, v76, v88
	v_exp_f32_e32 v241, v68
	v_sub_f32_e32 v68, v73, v217
	v_add_f32_e32 v82, v83, v82
	v_add_f32_e32 v83, v77, v91
	v_exp_f32_e32 v242, v68
	v_add_f32_e32 v66, v83, v82
	v_add_f32_e32 v67, v94, v95
	v_add_f32_e32 v66, v67, v66
	v_add_f32_e32 v67, v237, v238
	v_add_f32_e32 v66, v67, v66
	v_add_f32_e32 v67, v239, v240
	v_add_f32_e32 v66, v67, v66
	v_add_f32_e32 v67, v241, v242
	v_exp_f32_e32 v80, v80
	v_add_f32_e32 v83, v67, v66
	v_mov_b32_e32 v84, v83
	s_nop 1
	v_permlane32_swap_b32_e32 v84, v83
	v_cvt_pk_bf16_f32 v66, v78, v92
	v_cndmask_b32_e64 v82, v80, 1.0, vcc
	v_cvt_pk_bf16_f32 v67, v96, v230
	v_cvt_pk_bf16_f32 v68, v232, v233
	v_cvt_pk_bf16_f32 v69, v234, v236
	v_cvt_pk_bf16_f32 v70, v74, v75
	v_cvt_pk_bf16_f32 v71, v76, v77
	v_cvt_pk_bf16_f32 v72, v94, v237
	v_cvt_pk_bf16_f32 v73, v239, v241
	v_cvt_pk_bf16_f32 v74, v81, v93
	v_cvt_pk_bf16_f32 v75, v97, v231
	v_cvt_pk_bf16_f32 v76, v86, v87
	v_cvt_pk_bf16_f32 v77, v235, v85
	v_cvt_pk_bf16_f32 v78, v89, v90
	v_cvt_pk_bf16_f32 v79, v88, v91
	v_cvt_pk_bf16_f32 v80, v95, v238
	v_cvt_pk_bf16_f32 v81, v240, v242
	s_nop 0
	v_permlane32_swap_b32_e32 v66, v68
	v_permlane32_swap_b32_e32 v67, v69
	v_permlane32_swap_b32_e32 v70, v72
	v_permlane32_swap_b32_e32 v71, v73
	v_permlane32_swap_b32_e32 v74, v76
	v_permlane32_swap_b32_e32 v75, v77
	v_permlane32_swap_b32_e32 v78, v80
	v_permlane32_swap_b32_e32 v79, v81
	v_cmp_gt_f32_e32 vcc, 1.0, v82
	s_cbranch_vccz .LBB0_1051
	v_pk_mul_f32 v[64:65], v[64:65], v[82:83] op_sel_hi:[1,0]
	v_pk_mul_f32 v[62:63], v[62:63], v[82:83] op_sel_hi:[1,0]
	v_pk_mul_f32 v[60:61], v[60:61], v[82:83] op_sel_hi:[1,0]
	v_pk_mul_f32 v[58:59], v[58:59], v[82:83] op_sel_hi:[1,0]
	v_pk_mul_f32 v[56:57], v[56:57], v[82:83] op_sel_hi:[1,0]
	v_pk_mul_f32 v[54:55], v[54:55], v[82:83] op_sel_hi:[1,0]
	v_pk_mul_f32 v[52:53], v[52:53], v[82:83] op_sel_hi:[1,0]
	v_pk_mul_f32 v[50:51], v[50:51], v[82:83] op_sel_hi:[1,0]
	v_pk_mul_f32 v[48:49], v[48:49], v[82:83] op_sel_hi:[1,0]
	v_pk_mul_f32 v[46:47], v[46:47], v[82:83] op_sel_hi:[1,0]
	v_pk_mul_f32 v[44:45], v[44:45], v[82:83] op_sel_hi:[1,0]
	v_pk_mul_f32 v[42:43], v[42:43], v[82:83] op_sel_hi:[1,0]
	v_pk_mul_f32 v[40:41], v[40:41], v[82:83] op_sel_hi:[1,0]
	v_pk_mul_f32 v[38:39], v[38:39], v[82:83] op_sel_hi:[1,0]
	v_pk_mul_f32 v[36:37], v[36:37], v[82:83] op_sel_hi:[1,0]
	v_pk_mul_f32 v[34:35], v[34:35], v[82:83] op_sel_hi:[1,0]
	v_pk_mul_f32 v[32:33], v[32:33], v[82:83] op_sel_hi:[1,0]
	v_pk_mul_f32 v[30:31], v[30:31], v[82:83] op_sel_hi:[1,0]
	v_pk_mul_f32 v[28:29], v[28:29], v[82:83] op_sel_hi:[1,0]
	v_pk_mul_f32 v[26:27], v[26:27], v[82:83] op_sel_hi:[1,0]
	v_pk_mul_f32 v[24:25], v[24:25], v[82:83] op_sel_hi:[1,0]
	v_pk_mul_f32 v[22:23], v[22:23], v[82:83] op_sel_hi:[1,0]
	v_pk_mul_f32 v[20:21], v[20:21], v[82:83] op_sel_hi:[1,0]
	v_pk_mul_f32 v[18:19], v[18:19], v[82:83] op_sel_hi:[1,0]
	v_pk_mul_f32 v[16:17], v[16:17], v[82:83] op_sel_hi:[1,0]
	v_pk_mul_f32 v[14:15], v[14:15], v[82:83] op_sel_hi:[1,0]
	v_pk_mul_f32 v[12:13], v[12:13], v[82:83] op_sel_hi:[1,0]
	v_pk_mul_f32 v[10:11], v[10:11], v[82:83] op_sel_hi:[1,0]
	v_pk_mul_f32 v[8:9], v[8:9], v[82:83] op_sel_hi:[1,0]
	v_pk_mul_f32 v[6:7], v[6:7], v[82:83] op_sel_hi:[1,0]
	v_pk_mul_f32 v[4:5], v[4:5], v[82:83] op_sel_hi:[1,0]
	v_pk_mul_f32 v[2:3], v[2:3], v[82:83] op_sel_hi:[1,0]

; #define LAS __attribute__((address_space(3)))
; DI int crow(int r, int hi) { return (r & 3) + 8 * (r >> 2) + 4 * hi; }
; DI void qkt(f32x16& p0, f32x16& p1, const LAS char* Ks, const bf16x8* qr, int r32, int hi) {
;     for (int i = 0; i < 16; ++i) { p0[i] = 0.f; p1[i] = 0.f; }
; #pragma unroll
;     for (int d0 = 0; d0 < 8; ++d0) { const int cb = (d0 * 16 + hi * 8) * 2;
;         const bf16x8 b0 = *(const LAS bf16x8*)(Ks + KSWZ(r32, cb));
;         const bf16x8 b1 = *(const LAS bf16x8*)(Ks + KSWZ(32 + r32, cb));
;         p0 = __builtin_amdgcn_mfma_f32_32x32x16_bf16(b0, qr[d0], p0, 0, 0, 0);
;         p1 = __builtin_amdgcn_mfma_f32_32x32x16_bf16(b1, qr[d0], p1, 0, 0, 0); }
; }
; DI void phase_attn(const Params& P, int l, LAS unsigned char* lds) {
;     ...
;             for (int h2 = 0; h2 < 2; ++h2) {
;                 const int kp0 = (n - 1 + t) * 128 + h2 * 64;
;                 if (kp0 + 63 >= rq - 128 && kp0 <= rq + 159) {
;                     f32x16 p0, p1;
;                     qkt(p0, p1, Bf + h2 * 16384, qr, r32, hi);
;                     const LAS float* tq = tg + (kp0 - rq);
;                     float pmax = -1e30f;
; #pragma unroll
;                     for (int r = 0; r < 16; ++r) { p0[r] += tq[crow(r, hi)]; p1[r] += tq[32 + crow(r, hi)]; pmax = fmaxf(pmax, fmaxf(p0[r], p1[r])); }
.LBB0_1052:
	s_add_i32 s30, s28, 64
	s_addk_i32 s28, 0x7f
	s_cmp_lt_i32 s28, s86
	s_cselect_b64 s[28:29], -1, 0
	s_cmp_gt_i32 s30, s87
	s_cselect_b64 s[30:31], -1, 0
	s_or_b64 s[28:29], s[28:29], s[30:31]
	s_and_b64 vcc, exec, s[28:29]
	s_cbranch_vccnz .LBB0_1036
	ds_read_b128 v[66:69], v229 offset:16384
	ds_read_b128 v[82:85], v229 offset:24576
	ds_read_b128 v[230:233], v228 offset:16384
	ds_read_b128 v[234:237], v228 offset:24576
	ds_read_b128 v[246:249], v227 offset:16384
	ds_read_b128 v[250:253], v227 offset:24576
	s_waitcnt lgkmcnt(4)
	v_mfma_f32_32x32x16_bf16 v[66:81], v[66:69], v[126:129], 0
	v_mfma_f32_32x32x16_bf16 v[82:97], v[82:85], v[126:129], 0
	s_waitcnt lgkmcnt(2)
	v_mfma_f32_32x32x16_bf16 v[66:81], v[230:233], v[122:125], v[66:81]
	v_mfma_f32_32x32x16_bf16 v[82:97], v[234:237], v[122:125], v[82:97]
	ds_read_b128 v[228:231], v226 offset:16384
	ds_read_b128 v[232:235], v226 offset:24576
	s_waitcnt lgkmcnt(2)
	v_mfma_f32_32x32x16_bf16 v[66:81], v[246:249], v[118:121], v[66:81]
	v_mfma_f32_32x32x16_bf16 v[82:97], v[250:253], v[118:121], v[82:97]
	ds_read_b128 v[246:249], v225 offset:16384
	ds_read_b128 v[250:253], v225 offset:24576
	s_waitcnt lgkmcnt(2)
	v_mfma_f32_32x32x16_bf16 v[66:81], v[228:231], v[114:117], v[66:81]
	v_mfma_f32_32x32x16_bf16 v[82:97], v[232:235], v[114:117], v[82:97]
	ds_read_b128 v[226:229], v224 offset:16384
	ds_read_b128 v[230:233], v224 offset:24576
	s_waitcnt lgkmcnt(2)
	v_mfma_f32_32x32x16_bf16 v[66:81], v[246:249], v[110:113], v[66:81]
	v_mfma_f32_32x32x16_bf16 v[82:97], v[250:253], v[110:113], v[82:97]
	ds_read_b128 v[246:249], v223 offset:16384
	ds_read_b128 v[250:253], v223 offset:24576
	s_waitcnt lgkmcnt(2)
	v_mfma_f32_32x32x16_bf16 v[66:81], v[226:229], v[106:109], v[66:81]
	v_mfma_f32_32x32x16_bf16 v[82:97], v[230:233], v[106:109], v[82:97]
	ds_read_b128 v[224:227], v222 offset:16384
	ds_read_b128 v[228:231], v222 offset:24576
	v_add_u32_e32 v232, 0x20308, v221
	s_waitcnt lgkmcnt(2)
	v_mfma_f32_32x32x16_bf16 v[66:81], v[246:249], v[102:105], v[66:81]
	v_mfma_f32_32x32x16_bf16 v[82:97], v[250:253], v[102:105], v[82:97]
	v_add_u32_e32 v222, 0x20280, v221
	ds_read2_b32 v[222:223], v222 offset1:1
	s_waitcnt lgkmcnt(0)
	v_mfma_f32_32x32x16_bf16 v[66:81], v[224:227], v[98:101], v[66:81]
	v_add_u32_e32 v224, 0x20300, v221
	v_add_u32_e32 v226, 0x20288, v221
	ds_read2_b32 v[224:225], v224 offset1:1
	ds_read2_b32 v[226:227], v226 offset1:1
	ds_read2_b32 v[232:233], v232 offset1:1
	s_nop 6
	v_add_f32_e32 v222, v66, v222
	v_mfma_f32_32x32x16_bf16 v[82:97], v[228:231], v[98:101], v[82:97]
	v_add_f32_e32 v223, v67, v223
	s_waitcnt lgkmcnt(0)
	v_add_f32_e32 v226, v68, v226
	v_add_f32_e32 v227, v69, v227
	s_nop 7
	v_add_f32_e32 v224, v82, v224
	v_add_f32_e32 v225, v83, v225
	v_max_f32_e32 v66, v222, v224
	v_max_f32_e32 v67, v223, v225
	v_add_f32_e32 v228, v84, v232
	v_add_f32_e32 v229, v85, v233
	v_max3_f32 v66, v66, s57, v67
	v_max_f32_e32 v67, v226, v228
	v_max_f32_e32 v68, v227, v229
	v_max3_f32 v230, v66, v67, v68
	v_add_u32_e32 v66, 0x202a0, v221
	v_add_u32_e32 v68, 0x20320, v221
	ds_read2_b32 v[66:67], v66 offset1:1
	ds_read2_b32 v[68:69], v68 offset1:1
	v_add_u32_e32 v82, 0x202a8, v221
	v_add_u32_e32 v84, 0x20328, v221
	ds_read2_b32 v[82:83], v82 offset1:1
	ds_read2_b32 v[84:85], v84 offset1:1
	s_waitcnt lgkmcnt(0)
	v_add_f32_e32 v231, v70, v66
	v_add_f32_e32 v86, v86, v68
	v_add_f32_e32 v232, v71, v67
	v_add_f32_e32 v87, v87, v69
	v_max_f32_e32 v66, v231, v86
	v_max_f32_e32 v67, v232, v87
	v_add_f32_e32 v82, v72, v82
	v_add_f32_e32 v84, v88, v84
	v_add_f32_e32 v83, v73, v83
	v_add_f32_e32 v85, v89, v85
	v_max3_f32 v66, v230, v66, v67
	v_max_f32_e32 v67, v82, v84
	v_max_f32_e32 v68, v83, v85
	v_max3_f32 v88, v66, v67, v68
	v_add_u32_e32 v66, 0x202c0, v221
	v_add_u32_e32 v68, 0x20340, v221
	ds_read2_b32 v[66:67], v66 offset1:1
	ds_read2_b32 v[68:69], v68 offset1:1
	v_add_u32_e32 v70, 0x202c8, v221
	v_add_u32_e32 v72, 0x20348, v221
	ds_read2_b32 v[70:71], v70 offset1:1
	ds_read2_b32 v[72:73], v72 offset1:1
	s_waitcnt lgkmcnt(0)
	v_add_f32_e32 v74, v74, v66
	v_add_f32_e32 v89, v90, v68
	v_add_f32_e32 v75, v75, v67
	v_add_f32_e32 v90, v91, v69
	v_max_f32_e32 v66, v74, v89
	v_max_f32_e32 v67, v75, v90
	v_max3_f32 v66, v88, v66, v67
	v_add_f32_e32 v76, v76, v70
	v_add_f32_e32 v88, v92, v72
	v_add_f32_e32 v77, v77, v71
	v_add_f32_e32 v91, v93, v73
	v_max_f32_e32 v67, v76, v88
	v_max_f32_e32 v68, v77, v91
	v_max3_f32 v92, v66, v67, v68
	v_add_u32_e32 v66, 0x202e0, v221
	v_add_u32_e32 v68, 0x20360, v221
	ds_read2_b32 v[66:67], v66 offset1:1
	ds_read2_b32 v[68:69], v68 offset1:1
	v_add_u32_e32 v70, 0x202e8, v221
	v_add_u32_e32 v72, 0x20368, v221
	ds_read2_b32 v[70:71], v70 offset1:1
	ds_read2_b32 v[72:73], v72 offset1:1
	s_waitcnt lgkmcnt(0)
; DI int crow(int r, int hi) { return (r & 3) + 8 * (r >> 2) + 4 * hi; }
; DI void phase_attn(const Params& P, int l, LAS unsigned char* lds) {
;     ...
;                     for (int r = 0; r < 16; ++r) { p0[r] += tq[crow(r, hi)]; p1[r] += tq[32 + crow(r, hi)]; pmax = fmaxf(pmax, fmaxf(p0[r], p1[r])); }
;                     pmax = fmaxf(pmax, __shfl_xor(pmax, 32));
;                     float mn = m_run, alpha = 1.f;
;                     if (!__all(pmax - m_run <= 8.f)) { mn = fmaxf(m_run, pmax); alpha = __builtin_amdgcn_exp2f(m_run - mn); m_run = mn; }
;                     float ps = 0.f;
; #pragma unroll
;                     for (int r = 0; r < 16; ++r) { p0[r] = __builtin_amdgcn_exp2f(p0[r] - mn); p1[r] = __builtin_amdgcn_exp2f(p1[r] - mn); ps += p0[r] + p1[r]; }
;                     ps += __shfl_xor(ps, 32);
;                     l_run = l_run * alpha + ps;
;                     bf16x8 pa0, pa1, pa2, pa3;
;     ...
;                     PK4(p0, 0, pa0); PK4(p0, 8, pa1); PK4(p1, 0, pa2); PK4(p1, 8, pa3);
;     ...
;                     if (__any(alpha < 1.f)) {
; #pragma unroll
;                         for (int d = 0; d < 4; ++d)
; #pragma unroll
;                             for (int r = 0; r < 16; ++r) o[d][r] *= alpha; }
	v_add_f32_e32 v66, v78, v66
	v_add_f32_e32 v68, v94, v68
	v_add_f32_e32 v67, v79, v67
	v_add_f32_e32 v69, v95, v69
	v_max_f32_e32 v78, v66, v68
	v_max_f32_e32 v79, v67, v69
	v_add_f32_e32 v70, v80, v70
	v_add_f32_e32 v72, v96, v72
	v_add_f32_e32 v71, v81, v71
	v_add_f32_e32 v73, v97, v73
	v_max3_f32 v78, v92, v78, v79
	v_max_f32_e32 v79, v70, v72
	v_max_f32_e32 v80, v71, v73
	v_max3_f32 v78, v78, v79, v80
	v_mov_b32_e32 v80, v78
	s_nop 1
	v_permlane32_swap_b32_e32 v80, v78
	v_max_f32_e32 v78, v78, v80
	v_sub_f32_e32 v80, v78, v217
	v_cmp_ge_f32_e32 vcc, s58, v80
	s_cmp_eq_u64 vcc, exec
	v_max_f32_e32 v80, v217, v217
	v_max_f32_e32 v78, v80, v78
	s_cselect_b64 vcc, -1, 0
	v_sub_f32_e32 v80, v217, v78
	v_cndmask_b32_e32 v217, v78, v217, vcc
	v_sub_f32_e32 v78, v222, v217
	v_sub_f32_e32 v81, v224, v217
	v_exp_f32_e32 v78, v78
	v_exp_f32_e32 v81, v81
	v_sub_f32_e32 v92, v223, v217
	v_sub_f32_e32 v93, v225, v217
	v_exp_f32_e32 v92, v92
	v_exp_f32_e32 v93, v93
	v_sub_f32_e32 v96, v226, v217
	v_sub_f32_e32 v97, v228, v217
	v_exp_f32_e32 v96, v96
	v_exp_f32_e32 v97, v97
	v_sub_f32_e32 v221, v227, v217
	v_sub_f32_e32 v222, v229, v217
	v_exp_f32_e32 v221, v221
	v_exp_f32_e32 v222, v222
	v_sub_f32_e32 v223, v231, v217
	v_sub_f32_e32 v86, v86, v217
	v_sub_f32_e32 v82, v82, v217
	v_add_f32_e32 v94, v78, v81
	v_exp_f32_e32 v223, v223
	v_exp_f32_e32 v86, v86
	v_sub_f32_e32 v224, v232, v217
	v_sub_f32_e32 v87, v87, v217
	v_exp_f32_e32 v225, v82
	v_sub_f32_e32 v82, v84, v217
	v_add_f32_e32 v94, 0, v94
	v_add_f32_e32 v95, v92, v93
	v_exp_f32_e32 v224, v224
	v_exp_f32_e32 v87, v87
	v_exp_f32_e32 v226, v82
	v_sub_f32_e32 v82, v83, v217
	v_add_f32_e32 v94, v95, v94
	v_add_f32_e32 v95, v96, v97
	v_exp_f32_e32 v227, v82
	v_sub_f32_e32 v82, v85, v217
	v_add_f32_e32 v94, v95, v94
	v_add_f32_e32 v95, v221, v222
	v_exp_f32_e32 v85, v82
	v_sub_f32_e32 v74, v74, v217
	v_sub_f32_e32 v84, v89, v217
	v_add_f32_e32 v94, v95, v94
	v_add_f32_e32 v95, v223, v86
	v_exp_f32_e32 v74, v74
	v_exp_f32_e32 v89, v84
	v_sub_f32_e32 v75, v75, v217
	v_sub_f32_e32 v84, v90, v217
	v_add_f32_e32 v94, v95, v94
	v_add_f32_e32 v95, v224, v87
	v_exp_f32_e32 v75, v75
	v_exp_f32_e32 v90, v84
	v_sub_f32_e32 v76, v76, v217
	v_sub_f32_e32 v84, v88, v217
	v_sub_f32_e32 v66, v66, v217
	v_add_f32_e32 v82, v95, v94
	v_add_f32_e32 v83, v225, v226
	v_exp_f32_e32 v76, v76
	v_exp_f32_e32 v88, v84
	v_sub_f32_e32 v77, v77, v217
	v_sub_f32_e32 v84, v91, v217
	v_exp_f32_e32 v94, v66
	v_sub_f32_e32 v66, v68, v217
	v_add_f32_e32 v82, v83, v82
	v_add_f32_e32 v83, v227, v85
	v_exp_f32_e32 v77, v77
	v_exp_f32_e32 v91, v84
	v_exp_f32_e32 v95, v66
	v_sub_f32_e32 v66, v67, v217
	v_sub_f32_e32 v68, v70, v217
	v_add_f32_e32 v82, v83, v82
	v_add_f32_e32 v83, v74, v89
	v_exp_f32_e32 v228, v66
	v_sub_f32_e32 v66, v69, v217
	v_exp_f32_e32 v230, v68
	v_sub_f32_e32 v68, v72, v217
	v_add_f32_e32 v82, v83, v82
	v_add_f32_e32 v83, v75, v90
	v_exp_f32_e32 v229, v66
	v_exp_f32_e32 v231, v68
	v_sub_f32_e32 v68, v71, v217
	v_add_f32_e32 v82, v83, v82
	v_add_f32_e32 v83, v76, v88
	v_exp_f32_e32 v232, v68
	v_sub_f32_e32 v68, v73, v217
	v_add_f32_e32 v82, v83, v82
	v_add_f32_e32 v83, v77, v91
	v_exp_f32_e32 v233, v68
	v_add_f32_e32 v66, v83, v82
	v_add_f32_e32 v67, v94, v95
	v_add_f32_e32 v66, v67, v66
	v_add_f32_e32 v67, v228, v229
	v_add_f32_e32 v66, v67, v66
	v_add_f32_e32 v67, v230, v231
	v_add_f32_e32 v66, v67, v66
	v_add_f32_e32 v67, v232, v233
	v_exp_f32_e32 v80, v80
	v_add_f32_e32 v83, v67, v66
	v_mov_b32_e32 v84, v83
	s_nop 1
	v_permlane32_swap_b32_e32 v84, v83
	v_cvt_pk_bf16_f32 v66, v78, v92
	v_cndmask_b32_e64 v82, v80, 1.0, vcc
	v_cvt_pk_bf16_f32 v67, v96, v221
	v_cvt_pk_bf16_f32 v68, v223, v224
	v_cvt_pk_bf16_f32 v69, v225, v227
	v_cvt_pk_bf16_f32 v70, v74, v75
	v_cvt_pk_bf16_f32 v71, v76, v77
	v_cvt_pk_bf16_f32 v72, v94, v228
	v_cvt_pk_bf16_f32 v73, v230, v232
	v_cvt_pk_bf16_f32 v74, v81, v93
	v_cvt_pk_bf16_f32 v75, v97, v222
	v_cvt_pk_bf16_f32 v76, v86, v87
	v_cvt_pk_bf16_f32 v77, v226, v85
	v_cvt_pk_bf16_f32 v78, v89, v90
	v_cvt_pk_bf16_f32 v79, v88, v91
	v_cvt_pk_bf16_f32 v80, v95, v229
	v_cvt_pk_bf16_f32 v81, v231, v233
	s_nop 0
	v_permlane32_swap_b32_e32 v66, v68
	v_permlane32_swap_b32_e32 v67, v69
	v_permlane32_swap_b32_e32 v70, v72
	v_permlane32_swap_b32_e32 v71, v73
	v_permlane32_swap_b32_e32 v74, v76
	v_permlane32_swap_b32_e32 v75, v77
	v_permlane32_swap_b32_e32 v78, v80
	v_permlane32_swap_b32_e32 v79, v81
	v_cmp_gt_f32_e32 vcc, 1.0, v82
	s_cbranch_vccz .LBB0_1035
	v_pk_mul_f32 v[64:65], v[64:65], v[82:83] op_sel_hi:[1,0]
	v_pk_mul_f32 v[62:63], v[62:63], v[82:83] op_sel_hi:[1,0]
	v_pk_mul_f32 v[60:61], v[60:61], v[82:83] op_sel_hi:[1,0]
	v_pk_mul_f32 v[58:59], v[58:59], v[82:83] op_sel_hi:[1,0]
	v_pk_mul_f32 v[56:57], v[56:57], v[82:83] op_sel_hi:[1,0]
	v_pk_mul_f32 v[54:55], v[54:55], v[82:83] op_sel_hi:[1,0]
	v_pk_mul_f32 v[52:53], v[52:53], v[82:83] op_sel_hi:[1,0]
	v_pk_mul_f32 v[50:51], v[50:51], v[82:83] op_sel_hi:[1,0]
	v_pk_mul_f32 v[48:49], v[48:49], v[82:83] op_sel_hi:[1,0]
	v_pk_mul_f32 v[46:47], v[46:47], v[82:83] op_sel_hi:[1,0]
	v_pk_mul_f32 v[44:45], v[44:45], v[82:83] op_sel_hi:[1,0]
	v_pk_mul_f32 v[42:43], v[42:43], v[82:83] op_sel_hi:[1,0]
	v_pk_mul_f32 v[40:41], v[40:41], v[82:83] op_sel_hi:[1,0]
	v_pk_mul_f32 v[38:39], v[38:39], v[82:83] op_sel_hi:[1,0]
	v_pk_mul_f32 v[36:37], v[36:37], v[82:83] op_sel_hi:[1,0]
	v_pk_mul_f32 v[34:35], v[34:35], v[82:83] op_sel_hi:[1,0]
	v_pk_mul_f32 v[32:33], v[32:33], v[82:83] op_sel_hi:[1,0]
	v_pk_mul_f32 v[30:31], v[30:31], v[82:83] op_sel_hi:[1,0]
	v_pk_mul_f32 v[28:29], v[28:29], v[82:83] op_sel_hi:[1,0]
	v_pk_mul_f32 v[26:27], v[26:27], v[82:83] op_sel_hi:[1,0]
	v_pk_mul_f32 v[24:25], v[24:25], v[82:83] op_sel_hi:[1,0]
	v_pk_mul_f32 v[22:23], v[22:23], v[82:83] op_sel_hi:[1,0]
	v_pk_mul_f32 v[20:21], v[20:21], v[82:83] op_sel_hi:[1,0]
	v_pk_mul_f32 v[18:19], v[18:19], v[82:83] op_sel_hi:[1,0]
	v_pk_mul_f32 v[16:17], v[16:17], v[82:83] op_sel_hi:[1,0]
	v_pk_mul_f32 v[14:15], v[14:15], v[82:83] op_sel_hi:[1,0]
	v_pk_mul_f32 v[12:13], v[12:13], v[82:83] op_sel_hi:[1,0]
	v_pk_mul_f32 v[10:11], v[10:11], v[82:83] op_sel_hi:[1,0]
	v_pk_mul_f32 v[8:9], v[8:9], v[82:83] op_sel_hi:[1,0]
	v_pk_mul_f32 v[6:7], v[6:7], v[82:83] op_sel_hi:[1,0]
	v_pk_mul_f32 v[4:5], v[4:5], v[82:83] op_sel_hi:[1,0]
	v_pk_mul_f32 v[2:3], v[2:3], v[82:83] op_sel_hi:[1,0]
	s_branch .LBB0_1035
